# B far loop: selection-mask LDS read issued at the top of the tile instead of after QK (counted-wait/early-issue lever)
# baseline (speedup 1.0000x reference)
; #define LAS __attribute__((address_space(3)))
; template <int DQK, bool MB> ...
;     ...
;             for (int kk = 0; kk < KK; ++kk) kfa[kk] = *(const LAS bf16x8*)(kb + kk * 1024 + koff);
; #pragma unroll
;             for (int ks = 0; ks < 4; ++ks) {
;                 if (ks < 3) {
; #pragma unroll
;                     for (int kk = 0; kk < KK; ++kk) { const bf16x8 t = *(const LAS bf16x8*)(kb + ((ks + 1) * KK + kk) * 1024 + koff); if (ks & 1) kfa[kk] = t; else kfb[kk] = t; }
;                 }
;                 __builtin_amdgcn_sched_barrier(0);
;                 s[ks][0] = (f32x4){0.f, 0.f, 0.f, 0.f}; s[ks][1] = (f32x4){0.f, 0.f, 0.f, 0.f};
; #pragma unroll
;                 for (int kk = 0; kk < KK; ++kk) { const bf16x8 kf = (ks & 1) ? kfb[kk] : kfa[kk];
;                     const bf16x8 qa0 = qf[0][kk], qa1 = qf[1][kk];
;                     s[ks][0] = __builtin_amdgcn_mfma_f32_16x16x32_bf16(kf, qa0, s[ks][0], 0, 0, 0);
;                     s[ks][1] = __builtin_amdgcn_mfma_f32_16x16x32_bf16(kf, qa1, s[ks][1], 0, 0, 0); }
;                 __builtin_amdgcn_sched_barrier(0);
;             }
;         }
;         if (ST) { asm volatile("" ::: "memory"); __builtin_amdgcn_s_barrier(); asm volatile("" ::: "memory"); }
;         if (act) {
;             if (MB) {
;                 const unsigned long long mw0 = sm0[kt], mw1 = sm1[kt];
;                 if (pass == 0) {
; #pragma unroll
;                     for (int ks = 0; ks < 4; ++ks) { const unsigned b0 = (unsigned)(mw0 >> (16 * ks + 4 * q)) & 0xFu, b1 = (unsigned)(mw1 >> (16 * ks + 4 * q)) & 0xFu;
; #pragma unroll
;                         for (int j = 0; j < 4; ++j) { s[ks][0][j] = ((b0 >> j) & 1u) ? s[ks][0][j] + tbfar : -INFINITY; s[ks][1][j] = ((b1 >> j) & 1u) ? s[ks][1][j] + tbfar : -INFINITY; } }
.LBB0_665:
	v_mov_b32_e32 v238, s4
	ds_read2_b64 v[234:237], v238 offset1:32
	v_lshl_add_u32 v156, s45, 14, v181
	ds_read_b128 v[124:127], v156
	ds_read_b128 v[128:131], v156 offset:1024
	ds_read_b128 v[132:135], v156 offset:2048
	ds_read_b128 v[136:139], v156 offset:3072
	ds_read_b128 v[140:143], v156 offset:4096
	ds_read_b128 v[160:163], v156 offset:5120
	ds_read_b128 v[164:167], v156 offset:6144
	ds_read_b128 v[186:189], v156 offset:7168
	s_waitcnt lgkmcnt(7)
	v_mfma_f32_16x16x32_bf16 v[190:193], v[124:127], v[44:47], 0
	v_mfma_f32_16x16x32_bf16 v[124:127], v[124:127], v[60:63], 0
	s_waitcnt lgkmcnt(6)
	v_mfma_f32_16x16x32_bf16 v[190:193], v[128:131], v[64:67], v[190:193]
	v_mfma_f32_16x16x32_bf16 v[124:127], v[128:131], v[72:75], v[124:127]
	s_waitcnt lgkmcnt(5)
	v_mfma_f32_16x16x32_bf16 v[128:131], v[132:135], v[68:71], v[190:193]
	v_mfma_f32_16x16x32_bf16 v[124:127], v[132:135], v[76:79], v[124:127]
	s_waitcnt lgkmcnt(4)
	v_mfma_f32_16x16x32_bf16 v[128:131], v[136:139], v[80:83], v[128:131]
	v_mfma_f32_16x16x32_bf16 v[124:127], v[136:139], v[56:59], v[124:127]
	ds_read_b128 v[132:135], v156 offset:8192
	ds_read_b128 v[136:139], v156 offset:9216
	ds_read_b128 v[190:193], v156 offset:10240
	ds_read_b128 v[194:197], v156 offset:11264
	s_waitcnt lgkmcnt(7)
	v_mfma_f32_16x16x32_bf16 v[198:201], v[140:143], v[44:47], 0
	v_mfma_f32_16x16x32_bf16 v[140:143], v[140:143], v[60:63], 0
	s_waitcnt lgkmcnt(6)
	v_mfma_f32_16x16x32_bf16 v[198:201], v[160:163], v[64:67], v[198:201]
	v_mfma_f32_16x16x32_bf16 v[140:143], v[160:163], v[72:75], v[140:143]
	s_waitcnt lgkmcnt(5)
	v_mfma_f32_16x16x32_bf16 v[160:163], v[164:167], v[68:71], v[198:201]
	v_mfma_f32_16x16x32_bf16 v[140:143], v[164:167], v[76:79], v[140:143]
	s_waitcnt lgkmcnt(4)
	v_mfma_f32_16x16x32_bf16 v[160:163], v[186:189], v[80:83], v[160:163]
	v_mfma_f32_16x16x32_bf16 v[140:143], v[186:189], v[56:59], v[140:143]
	ds_read_b128 v[164:167], v156 offset:12288
	ds_read_b128 v[186:189], v156 offset:13312
	ds_read_b128 v[198:201], v156 offset:14336
	ds_read_b128 v[202:205], v156 offset:15360
	s_waitcnt lgkmcnt(7)
	v_mfma_f32_16x16x32_bf16 v[206:209], v[132:135], v[44:47], 0
	v_mfma_f32_16x16x32_bf16 v[132:135], v[132:135], v[60:63], 0
	s_waitcnt lgkmcnt(6)
	v_mfma_f32_16x16x32_bf16 v[206:209], v[136:139], v[64:67], v[206:209]
	v_mfma_f32_16x16x32_bf16 v[132:135], v[136:139], v[72:75], v[132:135]
	s_waitcnt lgkmcnt(5)
	v_mfma_f32_16x16x32_bf16 v[136:139], v[190:193], v[68:71], v[206:209]
	v_mfma_f32_16x16x32_bf16 v[132:135], v[190:193], v[76:79], v[132:135]
	s_waitcnt lgkmcnt(4)
	v_mfma_f32_16x16x32_bf16 v[136:139], v[194:197], v[80:83], v[136:139]
	v_mfma_f32_16x16x32_bf16 v[132:135], v[194:197], v[56:59], v[132:135]
	s_waitcnt lgkmcnt(3)
	v_mfma_f32_16x16x32_bf16 v[190:193], v[164:167], v[44:47], 0
	v_mfma_f32_16x16x32_bf16 v[164:167], v[164:167], v[60:63], 0
	s_waitcnt lgkmcnt(2)
	v_mfma_f32_16x16x32_bf16 v[164:167], v[186:189], v[72:75], v[164:167]
	v_mfma_f32_16x16x32_bf16 v[190:193], v[186:189], v[64:67], v[190:193]
	s_waitcnt lgkmcnt(1)
	v_mfma_f32_16x16x32_bf16 v[164:167], v[198:201], v[76:79], v[164:167]
	v_mfma_f32_16x16x32_bf16 v[186:189], v[198:201], v[68:71], v[190:193]
	s_waitcnt lgkmcnt(0)
	v_mfma_f32_16x16x32_bf16 v[164:167], v[202:205], v[56:59], v[164:167]
	v_mfma_f32_16x16x32_bf16 v[186:189], v[202:205], v[80:83], v[186:189]
	s_nop 6
	v_mov_b32_e32 v158, v164
	s_waitcnt lgkmcnt(0)
	v_lshrrev_b64 v[156:157], v150, v[236:237]
	v_bfe_i32 v243, v156, 0, 1
	v_bfe_i32 v244, v156, 1, 1
	v_bfi_b32 v168, v243, v158, v155
	v_bfe_i32 v245, v156, 2, 1
	v_bfi_b32 v169, v244, v165, v155
	v_bfe_i32 v246, v156, 3, 1
	v_bfi_b32 v166, v245, v166, v155
	s_mul_i32 s47, s45, 0x4400
	v_bfi_b32 v185, v246, v167, v155
	v_lshrrev_b64 v[156:157], v150, v[234:235]
	v_bfe_i32 v247, v156, 0, 1
	v_bfe_i32 v243, v156, 1, 1
	v_bfe_i32 v244, v156, 2, 1
	v_bfi_b32 v158, v247, v186, v155
	v_bfe_i32 v245, v156, 3, 1
	v_bfi_b32 v164, v243, v187, v155
	v_bfi_b32 v167, v244, v188, v155
	v_bfi_b32 v183, v245, v189, v155
	v_lshrrev_b64 v[156:157], v152, v[236:237]
	v_bfe_i32 v246, v156, 0, 1
	v_bfi_b32 v186, v246, v132, v155
	v_bfe_i32 v247, v156, 1, 1
	v_bfe_i32 v243, v156, 2, 1
	v_bfi_b32 v187, v247, v133, v155
	v_bfe_i32 v244, v156, 3, 1
	v_bfi_b32 v188, v243, v134, v155
	v_bfi_b32 v189, v244, v135, v155
	v_lshrrev_b64 v[132:133], v152, v[234:235]
	v_bfe_i32 v245, v132, 0, 1
	v_bfe_i32 v246, v132, 1, 1
	v_bfi_b32 v134, v245, v136, v155
	v_bfe_i32 v247, v132, 2, 1
	v_bfe_i32 v243, v132, 3, 1
	v_bfi_b32 v136, v246, v137, v155
	v_lshrrev_b32_e32 v135, v154, v236
	v_bfe_i32 v244, v135, 0, 1
	v_bfi_b32 v138, v247, v138, v155
	v_bfi_b32 v156, v243, v139, v155
	v_lshrrev_b64 v[132:133], v154, v[236:237]
	v_bfe_i32 v245, v132, 1, 1
	v_bfi_b32 v194, v244, v140, v155
	v_bfe_i32 v246, v132, 2, 1
	v_bfe_i32 v247, v132, 3, 1
	v_bfi_b32 v195, v245, v141, v155
	v_lshrrev_b32_e32 v135, v154, v234
	v_bfe_i32 v243, v135, 0, 1
	v_bfi_b32 v196, v246, v142, v155
	v_bfi_b32 v197, v247, v143, v155
	v_lshrrev_b64 v[132:133], v154, v[234:235]
	v_bfe_i32 v244, v132, 1, 1
	v_bfi_b32 v135, v243, v160, v155
	v_bfe_i32 v245, v132, 2, 1
	v_bfe_i32 v246, v132, 3, 1
	v_bfi_b32 v140, v244, v161, v155
	v_bfi_b32 v142, v245, v162, v155
	v_bfi_b32 v160, v246, v163, v155
	v_lshrrev_b64 v[132:133], v179, v[236:237]
	v_lshrrev_b32_e32 v133, v179, v236
	v_bfe_i32 v247, v133, 0, 1
	v_bfe_i32 v243, v132, 2, 1
	v_bfi_b32 v162, v247, v124, v155
	v_bfe_i32 v244, v132, 1, 1
	v_bfe_i32 v245, v132, 3, 1
	v_bfi_b32 v192, v244, v125, v155
	v_lshrrev_b64 v[124:125], v179, v[234:235]
	v_mov_b32_e32 v125, v128
	v_lshrrev_b32_e32 v128, v179, v234
	v_bfe_i32 v246, v128, 0, 1
; template <int DQK, bool MB> ...
;     ...
;             float alpha2[2];
; #pragma unroll
;             for (int ct = 0; ct < 2; ++ct) {
;                 float mx = -INFINITY;
; #pragma unroll
;                 for (int ks = 0; ks < 4; ++ks)
; #pragma unroll
;                     for (int j = 0; j < 4; ++j) mx = fmaxf(mx, s[ks][ct][j]);
;                 mx = fmaxf(mx, __shfl_xor(mx, 16)); mx = fmaxf(mx, __shfl_xor(mx, 32));
;                 const float mnew = fmaxf(mrow[ct], mx), alpha = __builtin_amdgcn_exp2f(mrow[ct] - mnew);
;                 mrow[ct] = mnew;
;                 float ps = 0.f;
; #pragma unroll
;                 for (int ks = 0; ks < 4; ++ks)
; #pragma unroll
;                     for (int j = 0; j < 4; ++j) { const float p = __builtin_amdgcn_exp2f(s[ks][ct][j] - mnew); s[ks][ct][j] = p; ps += p; }
;                 lsum[ct] = lsum[ct] * alpha + ps; alpha2[ct] = alpha;
;             }
;             {
; #pragma unroll
;                 for (int ct = 0; ct < 2; ++ct)
; #pragma unroll
;                     for (int dt = 0; dt < 8; ++dt) o[ct][dt] *= alpha2[ct];
	v_mov_b32_e32 v128, v129
	v_bfe_i32 v247, v124, 1, 1
	v_bfi_b32 v125, v246, v125, v155
	v_mov_b32_e32 v129, v130
	v_bfe_i32 v244, v124, 2, 1
	v_bfi_b32 v128, v247, v128, v155
	v_bfe_i32 v246, v124, 3, 1
	v_bfi_b32 v129, v244, v129, v155
	v_bfi_b32 v124, v246, v131, v155
	v_max3_f32 v130, v125, s79, v128
	v_max3_f32 v130, v130, v129, v124
	v_max3_f32 v130, v130, v135, v140
	v_max3_f32 v130, v130, v142, v160
	v_max3_f32 v130, v130, v134, v136
	v_max3_f32 v130, v130, v138, v156
	v_max3_f32 v130, v130, v158, v164
	v_max3_f32 v130, v130, v167, v183
	v_mov_b32_e32 v131, v130
	s_nop 1
	v_permlane16_swap_b32_e32 v131, v130
	v_max_f32_e32 v130, v130, v131
	v_mov_b32_e32 v131, v130
	v_bfi_b32 v126, v243, v126, v155
	s_nop 0
	v_permlane32_swap_b32_e32 v131, v130
	v_max_f32_e32 v182, v130, v131
	v_add_f32_e32 v182, v113, v182
	v_max_f32_e32 v182, v123, v182
	v_sub_f32_e32 v241, v182, v123
	v_cmp_lt_f32_e64 s[98:99], 4.0, v241
	s_nop 1
	v_cndmask_b32_e64 v182, v123, v182, s[98:99]
	v_sub_f32_e32 v241, v182, v113
	v_sub_f32_e32 v130, v123, v182
	v_sub_f32_e32 v123, v125, v241
	v_bfi_b32 v132, v245, v127, v155
	v_exp_f32_e32 v157, v123
	v_sub_f32_e32 v123, v128, v241
	v_max3_f32 v128, v162, s79, v192
	v_max3_f32 v128, v128, v126, v132
	v_exp_f32_e32 v143, v123
	v_sub_f32_e32 v123, v129, v241
	v_max3_f32 v128, v128, v194, v195
	v_exp_f32_e32 v141, v123
	v_sub_f32_e32 v123, v124, v241
	v_max3_f32 v128, v128, v196, v197
	v_exp_f32_e32 v139, v123
	v_sub_f32_e32 v123, v135, v241
	v_max3_f32 v128, v128, v186, v187
	v_exp_f32_e32 v137, v123
	v_sub_f32_e32 v123, v140, v241
	v_max3_f32 v128, v128, v188, v189
	v_exp_f32_e32 v135, v123
	v_sub_f32_e32 v123, v142, v241
	v_max3_f32 v128, v128, v168, v169
	v_exp_f32_e32 v133, v123
	v_sub_f32_e32 v123, v160, v241
	v_max3_f32 v128, v128, v166, v185
	v_exp_f32_e32 v131, v123
	v_sub_f32_e32 v123, v134, v241
	v_mov_b32_e32 v134, v128
	v_sub_f32_e32 v124, v158, v241
	v_exp_f32_e32 v165, v124
	v_permlane16_swap_b32_e32 v134, v128
	v_sub_f32_e32 v124, v164, v241
	v_exp_f32_e32 v161, v124
	v_max_f32_e32 v128, v128, v134
	v_mov_b32_e32 v134, v128
	v_sub_f32_e32 v124, v167, v241
	v_exp_f32_e32 v129, v123
	v_permlane32_swap_b32_e32 v134, v128
	v_sub_f32_e32 v123, v136, v241
	v_exp_f32_e32 v167, v124
	v_sub_f32_e32 v124, v183, v241
	v_max_f32_e32 v183, v128, v134
	v_add_f32_e32 v183, v113, v183
	v_max_f32_e32 v183, v122, v183
	v_sub_f32_e32 v242, v183, v122
	v_cmp_lt_f32_e64 s[100:101], 4.0, v242
	s_nop 1
	v_cndmask_b32_e64 v183, v122, v183, s[100:101]
	v_sub_f32_e32 v242, v183, v113
	v_exp_f32_e32 v127, v123
	v_sub_f32_e32 v123, v138, v241
	v_sub_f32_e32 v190, v122, v183
	v_sub_f32_e32 v122, v162, v242
	v_exp_f32_e32 v125, v123
	v_sub_f32_e32 v123, v156, v241
	v_exp_f32_e32 v156, v122
	v_sub_f32_e32 v122, v192, v242
	v_exp_f32_e32 v142, v122
	v_sub_f32_e32 v122, v126, v242
	v_exp_f32_e32 v140, v122
	v_sub_f32_e32 v122, v132, v242
	v_exp_f32_e32 v138, v122
	v_sub_f32_e32 v122, v194, v242
	v_exp_f32_e32 v136, v122
	v_sub_f32_e32 v122, v195, v242
	v_exp_f32_e32 v134, v122
	v_sub_f32_e32 v122, v196, v242
	v_sub_f32_e32 v160, v168, v242
	v_exp_f32_e32 v168, v190
	v_exp_f32_e32 v132, v122
	v_sub_f32_e32 v122, v197, v242
	v_exp_f32_e32 v158, v130
	v_exp_f32_e32 v130, v122
	v_sub_f32_e32 v122, v186, v242
	v_exp_f32_e32 v128, v122
	v_sub_f32_e32 v122, v187, v242
	v_exp_f32_e32 v126, v122
	v_sub_f32_e32 v122, v188, v242
	v_exp_f32_e32 v164, v160
	v_sub_f32_e32 v160, v169, v242
	v_sub_f32_e32 v162, v166, v242
	v_add_u32_e32 v169, s47, v180
	v_exp_f32_e32 v163, v124
	v_exp_f32_e32 v124, v122
	v_sub_f32_e32 v122, v189, v242
	v_exp_f32_e32 v166, v162
	v_sub_f32_e32 v162, v185, v242
	v_add_u32_e32 v185, 0x8000, v169
	v_add_u32_e32 v222, 0x8800, v169
	v_add_u32_e32 v223, 0x9000, v169
	v_add_u32_e32 v225, 0x9800, v169
	v_add_u32_e32 v230, 0xa000, v169
	v_add_u32_e32 v231, 0xa800, v169
	v_add_u32_e32 v232, 0xb000, v169
	v_add_u32_e32 v169, 0xb800, v169
	v_exp_f32_e32 v123, v123
	v_exp_f32_e32 v122, v122
	v_exp_f32_e32 v160, v160
	v_exp_f32_e32 v162, v162
	s_or_b64 s[98:99], s[98:99], s[100:101]
	s_cmp_eq_u64 s[98:99], 0
	s_cbranch_scc1 .Llazy_bf_skip
	v_pk_mul_f32 v[30:31], v[30:31], v[168:169] op_sel_hi:[1,0]
	v_pk_mul_f32 v[28:29], v[28:29], v[168:169] op_sel_hi:[1,0]
	v_pk_mul_f32 v[26:27], v[26:27], v[168:169] op_sel_hi:[1,0]
	v_pk_mul_f32 v[24:25], v[24:25], v[168:169] op_sel_hi:[1,0]
	v_pk_mul_f32 v[22:23], v[22:23], v[168:169] op_sel_hi:[1,0]
	v_pk_mul_f32 v[20:21], v[20:21], v[168:169] op_sel_hi:[1,0]
	v_pk_mul_f32 v[18:19], v[18:19], v[168:169] op_sel_hi:[1,0]
	v_pk_mul_f32 v[16:17], v[16:17], v[168:169] op_sel_hi:[1,0]
	v_pk_mul_f32 v[14:15], v[14:15], v[168:169] op_sel_hi:[1,0]
	v_pk_mul_f32 v[12:13], v[12:13], v[168:169] op_sel_hi:[1,0]
	v_pk_mul_f32 v[10:11], v[10:11], v[168:169] op_sel_hi:[1,0]
	v_pk_mul_f32 v[8:9], v[8:9], v[168:169] op_sel_hi:[1,0]
	v_pk_mul_f32 v[6:7], v[6:7], v[168:169] op_sel_hi:[1,0]
	v_pk_mul_f32 v[4:5], v[4:5], v[168:169] op_sel_hi:[1,0]
	v_pk_mul_f32 v[2:3], v[2:3], v[168:169] op_sel_hi:[1,0]
	v_pk_mul_f32 v[0:1], v[0:1], v[168:169] op_sel_hi:[1,0]
	v_pk_mul_f32 v[110:111], v[110:111], v[158:159] op_sel_hi:[1,0]
	v_pk_mul_f32 v[108:109], v[108:109], v[158:159] op_sel_hi:[1,0]
	v_pk_mul_f32 v[106:107], v[106:107], v[158:159] op_sel_hi:[1,0]
	v_pk_mul_f32 v[104:105], v[104:105], v[158:159] op_sel_hi:[1,0]
	v_pk_mul_f32 v[102:103], v[102:103], v[158:159] op_sel_hi:[1,0]
	v_pk_mul_f32 v[100:101], v[100:101], v[158:159] op_sel_hi:[1,0]
	v_pk_mul_f32 v[98:99], v[98:99], v[158:159] op_sel_hi:[1,0]
	v_pk_mul_f32 v[96:97], v[96:97], v[158:159] op_sel_hi:[1,0]
	v_pk_mul_f32 v[86:87], v[86:87], v[158:159] op_sel_hi:[1,0]
	v_pk_mul_f32 v[84:85], v[84:85], v[158:159] op_sel_hi:[1,0]
	v_pk_mul_f32 v[42:43], v[42:43], v[158:159] op_sel_hi:[1,0]
	v_pk_mul_f32 v[40:41], v[40:41], v[158:159] op_sel_hi:[1,0]
	v_pk_mul_f32 v[38:39], v[38:39], v[158:159] op_sel_hi:[1,0]
	v_pk_mul_f32 v[36:37], v[36:37], v[158:159] op_sel_hi:[1,0]
	v_pk_mul_f32 v[34:35], v[34:35], v[158:159] op_sel_hi:[1,0]
	v_pk_mul_f32 v[32:33], v[32:33], v[158:159] op_sel_hi:[1,0]
